# residual-add epilogue: the four per-block row-sum atomics of each 64-row group merged into one 64-lane atomic (8 -> 2 atomic instructions per wave per tile)
# speedup vs baseline: 1.0038x; 1.0008x over previous
.LBB0_286:
	v_readlane_b32 s80, v248, 26
	v_readlane_b32 s81, v248, 27
	s_andn2_b64 vcc, exec, s[80:81]
	s_nop 0
	v_cndmask_b32_e64 v152, 0, 1, s[80:81]
	v_cmp_ne_u32_e64 s[48:49], 1, v152
	s_cbranch_vccnz .LBB0_290
	v_mul_f32_e32 v152, v199, v199
	v_mul_f32_e32 v197, v197, v197
	v_fmac_f32_e32 v152, v198, v198
	v_fmac_f32_e32 v197, v196, v196
	v_add_f32_e32 v152, v152, v197
	v_mul_f32_e32 v196, v203, v203
	v_mul_f32_e32 v197, v201, v201
	v_mul_f32_e32 v149, v149, v149
	v_fmac_f32_e32 v196, v202, v202
	v_fmac_f32_e32 v197, v200, v200
	v_fmac_f32_e32 v149, v148, v148
	v_mul_f32_e32 v148, v151, v151
	v_mul_f32_e32 v145, v145, v145
	v_add_f32_e32 v196, v196, v197
	v_fmac_f32_e32 v148, v150, v150
	v_fmac_f32_e32 v145, v144, v144
	v_mul_f32_e32 v144, v147, v147
	v_add_f32_e32 v152, v152, v196
	v_add_f32_e32 v148, v149, v148
	v_fmac_f32_e32 v144, v146, v146
	v_add_f32_e32 v148, v152, v148
	v_add_f32_e32 v144, v145, v144
	v_add_f32_e32 v144, v144, v148
	v_mov_b32_e32 v145, v144
	s_nop 1
	v_permlane16_swap_b32_e32 v144, v145
	v_add_f32_e32 v144, v144, v145
	v_mov_b32_e32 v145, v144
	s_nop 1
	v_permlane32_swap_b32_e32 v144, v145
	v_add_f32_e32 v144, v144, v145
	v_cmp_eq_u32_e64 vcc, 0, v226
	s_nop 1
	v_cndmask_b32_e64 v247, v247, v144, vcc
.LBB0_289:
.LBB0_290:
	v_or_b32_e32 v144, 16, v194
	v_ashrrev_i32_e32 v145, 31, v144
	v_lshlrev_b64 v[144:145], 10, v[144:145]
	v_lshl_add_u64 v[196:197], v[144:145], 0, v[184:185]
	s_and_b64 vcc, exec, s[46:47]
	v_lshl_add_u64 v[210:211], v[196:197], 2, s[70:71]
	s_cbranch_vccnz .LBB0_475
	s_waitcnt vmcnt(1)
	v_mov_b32_e32 v148, v236
	v_mov_b32_e32 v149, v237
	v_mov_b32_e32 v150, v238
	v_mov_b32_e32 v151, v239
	v_mov_b32_e32 v144, v240
	v_mov_b32_e32 v145, v241
	v_mov_b32_e32 v146, v242
	v_mov_b32_e32 v147, v243
	global_load_dwordx4 v[236:239], v246, s[70:71] offset:512
	global_load_dwordx4 v[240:243], v246, s[70:71] offset:528
	v_lshl_add_u64 v[208:209], v[196:197], 1, s[68:69]
	s_cbranch_execnz .LBB0_293

.LBB0_300:
	s_and_b64 vcc, exec, s[48:49]
	s_cbranch_vccnz .LBB0_304
	v_mul_f32_e32 v152, v199, v199
	v_mul_f32_e32 v197, v197, v197
	v_fmac_f32_e32 v152, v198, v198
	v_fmac_f32_e32 v197, v196, v196
	v_add_f32_e32 v152, v152, v197
	v_mul_f32_e32 v196, v203, v203
	v_mul_f32_e32 v197, v201, v201
	v_mul_f32_e32 v149, v149, v149
	v_fmac_f32_e32 v196, v202, v202
	v_fmac_f32_e32 v197, v200, v200
	v_fmac_f32_e32 v149, v148, v148
	v_mul_f32_e32 v148, v151, v151
	v_mul_f32_e32 v145, v145, v145
	v_add_f32_e32 v196, v196, v197
	v_fmac_f32_e32 v148, v150, v150
	v_fmac_f32_e32 v145, v144, v144
	v_mul_f32_e32 v144, v147, v147
	v_add_f32_e32 v152, v152, v196
	v_add_f32_e32 v148, v149, v148
	v_fmac_f32_e32 v144, v146, v146
	v_add_f32_e32 v148, v152, v148
	v_add_f32_e32 v144, v145, v144
	v_add_f32_e32 v144, v144, v148
	v_mov_b32_e32 v145, v144
	s_nop 1
	v_permlane16_swap_b32_e32 v144, v145
	v_add_f32_e32 v144, v144, v145
	v_mov_b32_e32 v145, v144
	s_nop 1
	v_permlane32_swap_b32_e32 v144, v145
	v_add_f32_e32 v144, v144, v145
	v_cmp_eq_u32_e64 vcc, 8, v226
	s_nop 1
	v_cndmask_b32_e64 v247, v247, v144, vcc
.LBB0_303:
.LBB0_304:
	v_or_b32_e32 v144, 32, v194
	v_ashrrev_i32_e32 v145, 31, v144
	v_lshlrev_b64 v[144:145], 10, v[144:145]
	v_lshl_add_u64 v[196:197], v[144:145], 0, v[184:185]
	s_and_b64 vcc, exec, s[46:47]
	v_lshl_add_u64 v[210:211], v[196:197], 2, s[70:71]
	s_cbranch_vccnz .LBB0_477
	s_waitcnt vmcnt(1)
	v_mov_b32_e32 v148, v236
	v_mov_b32_e32 v149, v237
	v_mov_b32_e32 v150, v238
	v_mov_b32_e32 v151, v239
	v_mov_b32_e32 v144, v240
	v_mov_b32_e32 v145, v241
	v_mov_b32_e32 v146, v242
	v_mov_b32_e32 v147, v243
	global_load_dwordx4 v[236:239], v246, s[70:71] offset:512
	global_load_dwordx4 v[240:243], v246, s[70:71] offset:528
	v_lshl_add_u64 v[208:209], v[196:197], 1, s[68:69]
	s_cbranch_execnz .LBB0_307

.LBB0_314:
	s_and_b64 vcc, exec, s[48:49]
	s_cbranch_vccnz .LBB0_318
	v_mul_f32_e32 v152, v199, v199
	v_mul_f32_e32 v197, v197, v197
	v_fmac_f32_e32 v152, v198, v198
	v_fmac_f32_e32 v197, v196, v196
	v_add_f32_e32 v152, v152, v197
	v_mul_f32_e32 v196, v203, v203
	v_mul_f32_e32 v197, v201, v201
	v_mul_f32_e32 v149, v149, v149
	v_fmac_f32_e32 v196, v202, v202
	v_fmac_f32_e32 v197, v200, v200
	v_fmac_f32_e32 v149, v148, v148
	v_mul_f32_e32 v148, v151, v151
	v_mul_f32_e32 v145, v145, v145
	v_add_f32_e32 v196, v196, v197
	v_fmac_f32_e32 v148, v150, v150
	v_fmac_f32_e32 v145, v144, v144
	v_mul_f32_e32 v144, v147, v147
	v_add_f32_e32 v152, v152, v196
	v_add_f32_e32 v148, v149, v148
	v_fmac_f32_e32 v144, v146, v146
	v_add_f32_e32 v148, v152, v148
	v_add_f32_e32 v144, v145, v144
	v_add_f32_e32 v144, v144, v148
	v_mov_b32_e32 v145, v144
	s_nop 1
	v_permlane16_swap_b32_e32 v144, v145
	v_add_f32_e32 v144, v144, v145
	v_mov_b32_e32 v145, v144
	s_nop 1
	v_permlane32_swap_b32_e32 v144, v145
	v_add_f32_e32 v144, v144, v145
	v_cmp_eq_u32_e64 vcc, 16, v226
	s_nop 1
	v_cndmask_b32_e64 v247, v247, v144, vcc
.LBB0_317:
.LBB0_318:
	v_or_b32_e32 v144, 48, v194
	v_ashrrev_i32_e32 v145, 31, v144
	v_lshlrev_b64 v[144:145], 10, v[144:145]
	v_lshl_add_u64 v[196:197], v[144:145], 0, v[184:185]
	s_and_b64 vcc, exec, s[46:47]
	v_lshl_add_u64 v[210:211], v[196:197], 2, s[70:71]
	s_cbranch_vccnz .LBB0_479
	s_waitcnt vmcnt(1)
	v_mov_b32_e32 v148, v236
	v_mov_b32_e32 v149, v237
	v_mov_b32_e32 v150, v238
	v_mov_b32_e32 v151, v239
	v_mov_b32_e32 v144, v240
	v_mov_b32_e32 v145, v241
	v_mov_b32_e32 v146, v242
	v_mov_b32_e32 v147, v243
	global_load_dwordx4 v[236:239], v246, s[70:71] offset:512
	global_load_dwordx4 v[240:243], v246, s[70:71] offset:528
	v_lshl_add_u64 v[208:209], v[196:197], 1, s[68:69]
	s_cbranch_execnz .LBB0_321

.LBB0_328:
	s_and_b64 vcc, exec, s[48:49]
	s_cbranch_vccnz .LBB0_332
	v_mul_f32_e32 v152, v199, v199
	v_mul_f32_e32 v197, v197, v197
	v_fmac_f32_e32 v152, v198, v198
	v_fmac_f32_e32 v197, v196, v196
	v_add_f32_e32 v152, v152, v197
	v_mul_f32_e32 v196, v203, v203
	v_mul_f32_e32 v197, v201, v201
	v_mul_f32_e32 v149, v149, v149
	v_fmac_f32_e32 v196, v202, v202
	v_fmac_f32_e32 v197, v200, v200
	v_fmac_f32_e32 v149, v148, v148
	v_mul_f32_e32 v148, v151, v151
	v_mul_f32_e32 v145, v145, v145
	v_add_f32_e32 v196, v196, v197
	v_fmac_f32_e32 v148, v150, v150
	v_fmac_f32_e32 v145, v144, v144
	v_mul_f32_e32 v144, v147, v147
	v_add_f32_e32 v152, v152, v196
	v_add_f32_e32 v148, v149, v148
	v_fmac_f32_e32 v144, v146, v146
	v_add_f32_e32 v148, v152, v148
	v_add_f32_e32 v144, v145, v144
	v_add_f32_e32 v144, v144, v148
	v_mov_b32_e32 v145, v144
	s_nop 1
	v_permlane16_swap_b32_e32 v144, v145
	v_add_f32_e32 v144, v144, v145
	v_mov_b32_e32 v145, v144
	s_nop 1
	v_permlane32_swap_b32_e32 v144, v145
	v_add_f32_e32 v144, v144, v145
	v_readlane_b32 s80, v249, 62
	v_readlane_b32 s81, v249, 63
	v_cmp_eq_u32_e64 vcc, 24, v226
	s_nop 1
	v_cndmask_b32_e64 v247, v247, v144, vcc
	v_lshlrev_b32_e32 v147, 3, v226
	v_lshl_add_u32 v146, v174, 2, v147
	s_nop 1
	global_atomic_add_f32 v146, v247, s[80:81]
.LBB0_331:
.LBB0_332:
	v_lshlrev_b64 v[144:145], 10, v[194:195]
	v_lshl_add_u64 v[144:145], v[144:145], 0, v[184:185]
	s_mov_b64 s[80:81], 0x20000
	v_lshl_add_u64 v[196:197], v[144:145], 0, s[80:81]
	s_and_b64 vcc, exec, s[46:47]
	v_lshl_add_u64 v[210:211], v[196:197], 2, s[70:71]
	s_cbranch_vccnz .LBB0_481
	s_waitcnt vmcnt(1)
	v_mov_b32_e32 v148, v236
	v_mov_b32_e32 v149, v237
	v_mov_b32_e32 v150, v238
	v_mov_b32_e32 v151, v239
	v_mov_b32_e32 v144, v240
	v_mov_b32_e32 v145, v241
	v_mov_b32_e32 v146, v242
	v_mov_b32_e32 v147, v243
	global_load_dwordx4 v[236:239], v246, s[70:71] offset:512
	global_load_dwordx4 v[240:243], v246, s[70:71] offset:528
	v_lshl_add_u64 v[208:209], v[196:197], 1, s[68:69]
	s_cbranch_execnz .LBB0_335

.LBB0_342:
	s_and_b64 vcc, exec, s[48:49]
	s_cbranch_vccnz .LBB0_346
	v_mul_f32_e32 v152, v199, v199
	v_mul_f32_e32 v197, v197, v197
	v_fmac_f32_e32 v152, v198, v198
	v_fmac_f32_e32 v197, v196, v196
	v_add_f32_e32 v152, v152, v197
	v_mul_f32_e32 v196, v203, v203
	v_mul_f32_e32 v197, v201, v201
	v_mul_f32_e32 v149, v149, v149
	v_fmac_f32_e32 v196, v202, v202
	v_fmac_f32_e32 v197, v200, v200
	v_fmac_f32_e32 v149, v148, v148
	v_mul_f32_e32 v148, v151, v151
	v_mul_f32_e32 v145, v145, v145
	v_add_f32_e32 v196, v196, v197
	v_fmac_f32_e32 v148, v150, v150
	v_fmac_f32_e32 v145, v144, v144
	v_mul_f32_e32 v144, v147, v147
	v_add_f32_e32 v152, v152, v196
	v_add_f32_e32 v148, v149, v148
	v_fmac_f32_e32 v144, v146, v146
	v_add_f32_e32 v148, v152, v148
	v_add_f32_e32 v144, v145, v144
	v_add_f32_e32 v144, v144, v148
	v_mov_b32_e32 v145, v144
	s_nop 1
	v_permlane16_swap_b32_e32 v144, v145
	v_add_f32_e32 v144, v144, v145
	v_mov_b32_e32 v145, v144
	s_nop 1
	v_permlane32_swap_b32_e32 v144, v145
	v_add_f32_e32 v144, v144, v145
	v_cmp_eq_u32_e64 vcc, 0, v226
	s_nop 1
	v_cndmask_b32_e64 v247, v247, v144, vcc
.LBB0_345:
.LBB0_346:
	v_lshlrev_b64 v[144:145], 10, v[194:195]
	v_lshl_add_u64 v[144:145], v[144:145], 0, v[184:185]
	s_mov_b64 s[80:81], 0x24000
	v_lshl_add_u64 v[196:197], v[144:145], 0, s[80:81]
	s_and_b64 vcc, exec, s[46:47]
	v_lshl_add_u64 v[210:211], v[196:197], 2, s[70:71]
	s_cbranch_vccnz .LBB0_483
	s_waitcnt vmcnt(1)
	v_mov_b32_e32 v148, v236
	v_mov_b32_e32 v149, v237
	v_mov_b32_e32 v150, v238
	v_mov_b32_e32 v151, v239
	v_mov_b32_e32 v144, v240
	v_mov_b32_e32 v145, v241
	v_mov_b32_e32 v146, v242
	v_mov_b32_e32 v147, v243
	global_load_dwordx4 v[236:239], v246, s[70:71] offset:512
	global_load_dwordx4 v[240:243], v246, s[70:71] offset:528
	v_lshl_add_u64 v[208:209], v[196:197], 1, s[68:69]
	s_cbranch_execnz .LBB0_349

.LBB0_359:
.LBB0_360:
	v_lshlrev_b64 v[144:145], 10, v[194:195]
	v_lshl_add_u64 v[144:145], v[144:145], 0, v[184:185]
	s_mov_b64 s[80:81], 0x28000
	v_lshl_add_u64 v[196:197], v[144:145], 0, s[80:81]
	s_and_b64 vcc, exec, s[46:47]
	v_lshl_add_u64 v[210:211], v[196:197], 2, s[70:71]
	s_cbranch_vccnz .LBB0_485
	s_waitcnt vmcnt(1)
	v_mov_b32_e32 v148, v236
	v_mov_b32_e32 v149, v237
	v_mov_b32_e32 v150, v238
	v_mov_b32_e32 v151, v239
	v_mov_b32_e32 v144, v240
	v_mov_b32_e32 v145, v241
	v_mov_b32_e32 v146, v242
	v_mov_b32_e32 v147, v243
	global_load_dwordx4 v[236:239], v246, s[70:71] offset:512
	global_load_dwordx4 v[240:243], v246, s[70:71] offset:528
	v_lshl_add_u64 v[208:209], v[196:197], 1, s[68:69]
	s_cbranch_execnz .LBB0_363

.LBB0_373:
.LBB0_374:
	v_lshlrev_b64 v[144:145], 10, v[194:195]
	v_lshl_add_u64 v[144:145], v[144:145], 0, v[184:185]
	s_mov_b64 s[80:81], 0x2c000
	v_lshl_add_u64 v[194:195], v[144:145], 0, s[80:81]
	s_and_b64 vcc, exec, s[46:47]
	v_lshl_add_u64 v[196:197], v[194:195], 2, s[70:71]
	s_cbranch_vccnz .LBB0_487
	s_waitcnt vmcnt(1)
	v_mov_b32_e32 v148, v236
	v_mov_b32_e32 v149, v237
	v_mov_b32_e32 v150, v238
	v_mov_b32_e32 v151, v239
	v_mov_b32_e32 v144, v240
	v_mov_b32_e32 v145, v241
	v_mov_b32_e32 v146, v242
	v_mov_b32_e32 v147, v243
	global_load_dwordx4 v[236:239], v246, s[70:71] offset:512
	global_load_dwordx4 v[240:243], v246, s[70:71] offset:528
	s_mov_b32 s81, s23
	v_lshl_add_u64 v[198:199], v[194:195], 1, s[68:69]
	s_cbranch_execnz .LBB0_377

.LBB0_384:
	s_and_b64 vcc, exec, s[48:49]
	s_cbranch_vccnz .LBB0_388
	v_mul_f32_e32 v136, v149, v149
	v_mul_f32_e32 v137, v151, v151
	v_fmac_f32_e32 v136, v148, v148
	v_fmac_f32_e32 v137, v150, v150
	v_mul_f32_e32 v129, v129, v129
	v_add_f32_e32 v136, v136, v137
	v_mul_f32_e32 v137, v145, v145
	v_mul_f32_e32 v138, v147, v147
	v_fmac_f32_e32 v129, v128, v128
	v_mul_f32_e32 v128, v131, v131
	v_fmac_f32_e32 v137, v144, v144
	v_fmac_f32_e32 v138, v146, v146
	v_fmac_f32_e32 v128, v130, v130
	v_add_f32_e32 v137, v137, v138
	v_add_f32_e32 v128, v129, v128
	v_mul_f32_e32 v129, v133, v133
	v_mul_f32_e32 v130, v135, v135
	v_add_f32_e32 v136, v136, v137
	v_fmac_f32_e32 v129, v132, v132
	v_fmac_f32_e32 v130, v134, v134
	v_add_f32_e32 v128, v136, v128
	v_add_f32_e32 v129, v129, v130
	v_add_f32_e32 v128, v129, v128
	v_mov_b32_e32 v129, v128
	s_nop 1
	v_permlane16_swap_b32_e32 v128, v129
	v_add_f32_e32 v128, v128, v129
	v_mov_b32_e32 v129, v128
	s_nop 1
	v_permlane32_swap_b32_e32 v128, v129
	v_add_f32_e32 v128, v128, v129
	v_readlane_b32 s46, v249, 62
	v_readlane_b32 s47, v249, 63
	v_cmp_eq_u32_e64 s[44:45], 24, v226
	s_nop 1
	v_cndmask_b32_e64 v247, v247, v128, s[44:45]
	v_lshlrev_b32_e32 v131, 3, v226
	v_lshl_add_u32 v130, v174, 2, v131
	s_nop 1
	global_atomic_add_f32 v130, v247, s[46:47] offset:512
.LBB0_387:
.LBB0_388:
	s_branch .LBB0_404
